# E25: P4 EpiUp conv tap/bias words loaded at the unit-loop head (v232-v235 live across the K-loop); the epilogue has no vector-memory wait left, so it no longer drains the next unit's first K-tiles
# speedup vs baseline: 1.0016x; 1.0016x over previous
.LBB0_799:
	s_ashr_i32 s75, s74, 31
	s_lshl_b64 s[10:11], s[74:75], 20
	v_readlane_b32 s12, v250, 4
	v_readlane_b32 s13, v250, 5
	s_add_u32 s76, s12, s10
	s_addc_u32 s77, s13, s11
	s_and_b64 s[10:11], s[2:3], exec
	s_cselect_b32 s5, s77, s9
	s_cselect_b32 s10, s76, s8
	s_ashr_i32 s73, s72, 31
	s_lshl_b64 s[78:79], s[72:73], 20
	v_readlane_b32 s12, v251, 54
	v_readlane_b32 s13, v251, 55
	s_add_u32 s84, s12, s78
	s_addc_u32 s85, s13, s79
	s_and_b64 s[78:79], s[2:3], exec
	s_cselect_b32 s11, s85, s7
	s_cselect_b32 s73, s84, s6
	s_add_u32 s75, s6, 0x100
	s_addc_u32 s78, s7, 0
	s_add_u32 s6, s8, 0x80080
	v_mov_b32_e32 v68, 0
	s_addc_u32 s7, s9, 0
	s_mov_b32 s8, -2
	v_mov_b32_e32 v69, v68
	v_mov_b32_e32 v70, v68
	v_mov_b32_e32 v71, v68
	v_mov_b32_e32 v60, v68
	v_mov_b32_e32 v61, v68
	v_mov_b32_e32 v62, v68
	v_mov_b32_e32 v63, v68
	v_mov_b32_e32 v36, v68
	v_mov_b32_e32 v37, v68
	v_mov_b32_e32 v38, v68
	v_mov_b32_e32 v39, v68
	v_mov_b32_e32 v76, v68
	v_mov_b32_e32 v77, v68
	v_mov_b32_e32 v78, v68
	v_mov_b32_e32 v79, v68
	v_mov_b32_e32 v32, v68
	v_mov_b32_e32 v33, v68
	v_mov_b32_e32 v34, v68
	v_mov_b32_e32 v35, v68
	v_mov_b32_e32 v100, v68
	v_mov_b32_e32 v101, v68
	v_mov_b32_e32 v102, v68
	v_mov_b32_e32 v103, v68
	v_mov_b32_e32 v40, v68
	v_mov_b32_e32 v41, v68
	v_mov_b32_e32 v42, v68
	v_mov_b32_e32 v43, v68
	v_mov_b32_e32 v104, v68
	v_mov_b32_e32 v105, v68
	v_mov_b32_e32 v106, v68
	v_mov_b32_e32 v107, v68
	v_mov_b32_e32 v44, v68
	v_mov_b32_e32 v45, v68
	v_mov_b32_e32 v46, v68
	v_mov_b32_e32 v47, v68
	v_mov_b32_e32 v108, v68
	v_mov_b32_e32 v109, v68
	v_mov_b32_e32 v110, v68
	v_mov_b32_e32 v111, v68
	v_mov_b32_e32 v12, v68
	v_mov_b32_e32 v13, v68
	v_mov_b32_e32 v14, v68
	v_mov_b32_e32 v15, v68
	v_mov_b32_e32 v64, v68
	v_mov_b32_e32 v65, v68
	v_mov_b32_e32 v66, v68
	v_mov_b32_e32 v67, v68
	v_mov_b32_e32 v8, v68
	v_mov_b32_e32 v9, v68
	v_mov_b32_e32 v10, v68
	v_mov_b32_e32 v11, v68
	v_mov_b32_e32 v56, v68
	v_mov_b32_e32 v57, v68
	v_mov_b32_e32 v58, v68
	v_mov_b32_e32 v59, v68
	v_mov_b32_e32 v4, v68
	v_mov_b32_e32 v5, v68
	v_mov_b32_e32 v6, v68
	v_mov_b32_e32 v7, v68
	v_mov_b32_e32 v52, v68
	v_mov_b32_e32 v53, v68
	v_mov_b32_e32 v54, v68
	v_mov_b32_e32 v55, v68
	v_mov_b32_e32 v0, v68
	v_mov_b32_e32 v1, v68
	v_mov_b32_e32 v2, v68
	v_mov_b32_e32 v3, v68
	v_mov_b32_e32 v48, v68
	v_mov_b32_e32 v49, v68
	v_mov_b32_e32 v50, v68
	v_mov_b32_e32 v51, v68
	v_mov_b32_e32 v112, v68
	s_waitcnt lgkmcnt(0)
	v_mov_b32_e32 v113, v68
	v_mov_b32_e32 v114, v68
	v_mov_b32_e32 v115, v68
	v_mov_b32_e32 v80, v68
	v_mov_b32_e32 v81, v68
	v_mov_b32_e32 v82, v68
	v_mov_b32_e32 v83, v68
	v_mov_b32_e32 v116, v68
	v_mov_b32_e32 v117, v68
	v_mov_b32_e32 v118, v68
	v_mov_b32_e32 v119, v68
	v_mov_b32_e32 v72, v68
	v_mov_b32_e32 v73, v68
	v_mov_b32_e32 v74, v68
	v_mov_b32_e32 v75, v68
	v_mov_b32_e32 v120, v68
	v_mov_b32_e32 v121, v68
	v_mov_b32_e32 v122, v68
	v_mov_b32_e32 v123, v68
	v_mov_b32_e32 v124, v68
	v_mov_b32_e32 v125, v68
	v_mov_b32_e32 v126, v68
	v_mov_b32_e32 v127, v68
	v_mov_b32_e32 v28, v68
	v_mov_b32_e32 v29, v68
	v_mov_b32_e32 v30, v68
	v_mov_b32_e32 v31, v68
	v_mov_b32_e32 v96, v68
	v_mov_b32_e32 v97, v68
	v_mov_b32_e32 v98, v68
	v_mov_b32_e32 v99, v68
	v_mov_b32_e32 v24, v68
	v_mov_b32_e32 v25, v68
	v_mov_b32_e32 v26, v68
	v_mov_b32_e32 v27, v68
	v_mov_b32_e32 v92, v68
	v_mov_b32_e32 v93, v68
	v_mov_b32_e32 v94, v68
	v_mov_b32_e32 v95, v68
	v_mov_b32_e32 v20, v68
	v_mov_b32_e32 v21, v68
	v_mov_b32_e32 v22, v68
	v_mov_b32_e32 v23, v68
	v_mov_b32_e32 v88, v68
	v_mov_b32_e32 v89, v68
	v_mov_b32_e32 v90, v68
	v_mov_b32_e32 v91, v68
	v_mov_b32_e32 v16, v68
	v_mov_b32_e32 v17, v68
	v_mov_b32_e32 v18, v68
	v_mov_b32_e32 v19, v68
	v_mov_b32_e32 v84, v68
	v_mov_b32_e32 v85, v68
	v_mov_b32_e32 v86, v68
	v_mov_b32_e32 v87, v68
	v_readlane_b32 s98, v251, 42
	s_cmp_lt_u32 s98, 4
	s_cbranch_scc0 .Lcm4_skip
	v_mbcnt_lo_u32_b32 v230, -1, 0
	v_mbcnt_hi_u32_b32 v230, -1, v230
	v_lshlrev_b32_e32 v230, 2, v230
	s_lshr_b32 s99, s98, 1
	s_mul_i32 s99, s99, 0xac00
	s_and_b32 s100, s98, 1
	s_lshl_b32 s100, s100, 8
	s_add_i32 s99, s99, s100
	s_lshl_b32 s100, s4, 9
	s_add_i32 s99, s99, s100
	v_readlane_b32 s100, v251, 19
	v_readlane_b32 s101, v251, 20
	s_add_u32 s100, s100, 0x40000
	s_addc_u32 s101, s101, 0
	s_add_u32 s100, s100, s99
	s_addc_u32 s101, s101, 0
	s_lshl_b32 s99, s98, 8
	s_add_i32 m0, s99, 0x21000
	s_nop 0
	global_load_lds_dword v230, s[100:101]
	v_mbcnt_lo_u32_b32 v231, -1, 0
	v_mbcnt_hi_u32_b32 v231, -1, v231
	s_lshl_b32 s99, s98, 6
	v_add_u32_e32 v231, s99, v231
	s_cmp_lt_u32 s98, 2
	s_cselect_b32 s99, 0, 0x2a80
	s_lshl_b32 s100, s4, 7
	s_add_i32 s99, s99, s100
	v_add_u32_e32 v231, s99, v231
	v_lshlrev_b32_e32 v231, 2, v231
	v_readlane_b32 s100, v251, 35
	v_readlane_b32 s101, v251, 36
	s_nop 4
	global_load_dword v232, v231, s[100:101]
	s_add_u32 s98, s100, 0x15800
	s_addc_u32 s99, s101, 0
	global_load_dword v233, v231, s[98:99]
	s_add_u32 s98, s100, 0x2b000
	s_addc_u32 s99, s101, 0
	global_load_dword v234, v231, s[98:99]
	v_readlane_b32 s98, v251, 5
	v_readlane_b32 s99, v251, 6
	s_nop 4
	global_load_dword v235, v231, s[98:99]

.LBB0_807:
	s_lshl_b32 s4, s4, 7
	s_ashr_i32 s5, s4, 31
	v_ashrrev_i32_e32 v147, 4, v128
	s_lshl_b64 s[6:7], s[4:5], 2
	v_lshlrev_b32_e32 v140, 3, v147
	s_add_u32 s6, s59, s6
	v_and_b32_e32 v191, 15, v128
	v_ashrrev_i32_e32 v141, 31, v140
	s_addc_u32 s7, s24, s7
	v_lshl_add_u32 v128, v191, 2, s25
	v_lshl_add_u64 v[132:133], v[140:141], 2, s[6:7]
	ds_read2_b32 v[144:145], v128 offset1:16
	ds_read2_b32 v[142:143], v128 offset0:32 offset1:48
	ds_read2_b32 v[138:139], v128 offset0:128 offset1:144
	ds_read2_b32 v[136:137], v128 offset0:160 offset1:176
	s_lshl_b32 s98, s69, 2
	s_add_i32 s98, s98, 0x21000
	v_lshl_add_u32 v230, v140, 2, s98
	ds_read_b128 v[128:131], v230
	v_cvt_f32_i32_e32 v85, v85
	v_cvt_f32_i32_e32 v84, v84
	v_cvt_f32_i32_e32 v89, v89
	v_cvt_f32_i32_e32 v88, v88
	v_cvt_f32_i32_e32 v87, v87
	v_cvt_f32_i32_e32 v86, v86
	v_cvt_f32_i32_e32 v93, v93
	v_cvt_f32_i32_e32 v92, v92
	v_cvt_f32_i32_e32 v91, v91
	v_cvt_f32_i32_e32 v90, v90
	s_waitcnt lgkmcnt(0)
	v_mov_b32_e32 v148, v145
	v_cvt_f32_i32_e32 v95, v95
	v_cvt_f32_i32_e32 v94, v94
	v_cvt_f32_i32_e32 v97, v97
	v_cvt_f32_i32_e32 v96, v96
	v_cvt_f32_i32_e32 v99, v99
	v_cvt_f32_i32_e32 v98, v98
	v_cvt_f32_i32_e32 v49, v49
	v_cvt_f32_i32_e32 v48, v48
	v_cvt_f32_i32_e32 v51, v51
	v_cvt_f32_i32_e32 v50, v50
	v_cvt_f32_i32_e32 v53, v53
	v_cvt_f32_i32_e32 v52, v52
	v_cvt_f32_i32_e32 v55, v55
	v_cvt_f32_i32_e32 v54, v54
	v_cvt_f32_i32_e32 v57, v57
	v_cvt_f32_i32_e32 v56, v56
	v_cvt_f32_i32_e32 v59, v59
	v_cvt_f32_i32_e32 v58, v58
	v_cvt_f32_i32_e32 v65, v65
	v_cvt_f32_i32_e32 v64, v64
	v_cvt_f32_i32_e32 v67, v67
	v_cvt_f32_i32_e32 v66, v66
	v_mov_b32_e32 v146, v137
	s_waitcnt lgkmcnt(0)
	v_pk_mul_f32 v[150:151], v[144:145], v[128:129] op_sel_hi:[0,1]
	v_pk_mul_f32 v[84:85], v[150:151], v[84:85]
	v_pk_mul_f32 v[150:151], v[148:149], v[128:129] op_sel_hi:[0,1]
	v_pk_mul_f32 v[134:135], v[144:145], v[130:131] op_sel_hi:[0,1]
	v_pk_mul_f32 v[88:89], v[150:151], v[88:89]
	v_pk_mul_f32 v[150:151], v[142:143], v[128:129] op_sel_hi:[0,1]
	v_pk_mul_f32 v[86:87], v[134:135], v[86:87]
	v_pk_mul_f32 v[134:135], v[148:149], v[130:131] op_sel_hi:[0,1]
	v_pk_mul_f32 v[92:93], v[150:151], v[92:93]
	v_mov_b32_e32 v150, v143
	v_pk_mul_f32 v[90:91], v[134:135], v[90:91]
	v_pk_mul_f32 v[134:135], v[142:143], v[130:131] op_sel_hi:[0,1]
	v_pk_mul_f32 v[152:153], v[150:151], v[128:129] op_sel_hi:[0,1]
	v_pk_mul_f32 v[94:95], v[134:135], v[94:95]
	v_pk_mul_f32 v[134:135], v[150:151], v[130:131] op_sel_hi:[0,1]
	v_pk_mul_f32 v[96:97], v[152:153], v[96:97]
	v_pk_mul_f32 v[152:153], v[138:139], v[128:129] op_sel_hi:[0,1]
	v_pk_mul_f32 v[98:99], v[134:135], v[98:99]
	v_pk_mul_f32 v[134:135], v[138:139], v[130:131] op_sel_hi:[0,1]
	v_pk_mul_f32 v[48:49], v[152:153], v[48:49]
	v_mov_b32_e32 v152, v139
	v_pk_mul_f32 v[50:51], v[134:135], v[50:51]
	v_pk_mul_f32 v[134:135], v[152:153], v[130:131] op_sel_hi:[0,1]
	v_pk_mul_f32 v[154:155], v[152:153], v[128:129] op_sel_hi:[0,1]
	v_pk_mul_f32 v[54:55], v[134:135], v[54:55]
	v_pk_mul_f32 v[52:53], v[154:155], v[52:53]
	v_pk_mul_f32 v[134:135], v[136:137], v[130:131] op_sel_hi:[0,1]
	v_pk_mul_f32 v[154:155], v[136:137], v[128:129] op_sel_hi:[0,1]
	v_pk_mul_f32 v[130:131], v[130:131], v[146:147] op_sel_hi:[1,0]
	v_pk_mul_f32 v[128:129], v[128:129], v[146:147] op_sel_hi:[1,0]
	v_pk_mul_f32 v[58:59], v[134:135], v[58:59]
	v_pk_mul_f32 v[56:57], v[154:155], v[56:57]
	v_pk_mul_f32 v[66:67], v[130:131], v[66:67]
	v_pk_mul_f32 v[64:65], v[128:129], v[64:65]
	s_nop 0
	ds_read_b128 v[128:131], v230 offset:16
	v_cvt_f32_i32_e32 v17, v17
	v_cvt_f32_i32_e32 v16, v16
	v_cvt_f32_i32_e32 v19, v19
	v_cvt_f32_i32_e32 v18, v18
	v_cvt_f32_i32_e32 v21, v21
	v_cvt_f32_i32_e32 v20, v20
	v_cvt_f32_i32_e32 v23, v23
	v_cvt_f32_i32_e32 v22, v22
	v_cvt_f32_i32_e32 v25, v25
	v_cvt_f32_i32_e32 v24, v24
	v_cvt_f32_i32_e32 v27, v27
	v_cvt_f32_i32_e32 v26, v26
	v_cvt_f32_i32_e32 v29, v29
	v_cvt_f32_i32_e32 v28, v28
	v_cvt_f32_i32_e32 v31, v31
	v_cvt_f32_i32_e32 v30, v30
	v_cvt_f32_i32_e32 v1, v1
	v_cvt_f32_i32_e32 v0, v0
	v_cvt_f32_i32_e32 v3, v3
	v_cvt_f32_i32_e32 v2, v2
	v_cvt_f32_i32_e32 v5, v5
	v_cvt_f32_i32_e32 v4, v4
	v_cvt_f32_i32_e32 v7, v7
	v_cvt_f32_i32_e32 v6, v6
	v_cvt_f32_i32_e32 v9, v9
	v_cvt_f32_i32_e32 v8, v8
	v_cvt_f32_i32_e32 v11, v11
	v_cvt_f32_i32_e32 v10, v10
	v_cvt_f32_i32_e32 v13, v13
	v_cvt_f32_i32_e32 v12, v12
	v_cvt_f32_i32_e32 v15, v15
	v_cvt_f32_i32_e32 v14, v14
	s_waitcnt lgkmcnt(0)
	v_pk_mul_f32 v[134:135], v[144:145], v[130:131] op_sel_hi:[0,1]
	v_pk_mul_f32 v[154:155], v[144:145], v[128:129] op_sel_hi:[0,1]
	v_pk_mul_f32 v[18:19], v[134:135], v[18:19]
	v_pk_mul_f32 v[16:17], v[154:155], v[16:17]
	v_pk_mul_f32 v[134:135], v[148:149], v[130:131] op_sel_hi:[0,1]
	v_pk_mul_f32 v[154:155], v[148:149], v[128:129] op_sel_hi:[0,1]
	v_pk_mul_f32 v[22:23], v[134:135], v[22:23]
	v_pk_mul_f32 v[20:21], v[154:155], v[20:21]
	v_pk_mul_f32 v[134:135], v[142:143], v[130:131] op_sel_hi:[0,1]
	v_pk_mul_f32 v[154:155], v[142:143], v[128:129] op_sel_hi:[0,1]
	v_pk_mul_f32 v[26:27], v[134:135], v[26:27]
	v_pk_mul_f32 v[24:25], v[154:155], v[24:25]
	v_pk_mul_f32 v[134:135], v[150:151], v[130:131] op_sel_hi:[0,1]
	v_pk_mul_f32 v[154:155], v[150:151], v[128:129] op_sel_hi:[0,1]
	v_pk_mul_f32 v[30:31], v[134:135], v[30:31]
	v_pk_mul_f32 v[28:29], v[154:155], v[28:29]
	v_pk_mul_f32 v[134:135], v[138:139], v[130:131] op_sel_hi:[0,1]
	v_pk_mul_f32 v[154:155], v[138:139], v[128:129] op_sel_hi:[0,1]
	v_pk_mul_f32 v[2:3], v[134:135], v[2:3]
	v_pk_mul_f32 v[0:1], v[154:155], v[0:1]
	v_pk_mul_f32 v[134:135], v[152:153], v[130:131] op_sel_hi:[0,1]
	v_pk_mul_f32 v[154:155], v[152:153], v[128:129] op_sel_hi:[0,1]
	v_pk_mul_f32 v[6:7], v[134:135], v[6:7]
	v_pk_mul_f32 v[4:5], v[154:155], v[4:5]
	v_pk_mul_f32 v[134:135], v[136:137], v[130:131] op_sel_hi:[0,1]
	v_pk_mul_f32 v[154:155], v[136:137], v[128:129] op_sel_hi:[0,1]
	v_pk_mul_f32 v[130:131], v[146:147], v[130:131] op_sel_hi:[0,1]
	v_pk_mul_f32 v[128:129], v[146:147], v[128:129] op_sel_hi:[0,1]
	v_pk_mul_f32 v[10:11], v[134:135], v[10:11]
	v_pk_mul_f32 v[8:9], v[154:155], v[8:9]
	v_pk_mul_f32 v[14:15], v[130:131], v[14:15]
	v_pk_mul_f32 v[12:13], v[128:129], v[12:13]
	s_nop 0
	s_mov_b32 s5, 0xa000
	v_add_co_u32_e32 v154, vcc, s5, v132
	v_cvt_f32_i32_e32 v125, v125
	s_nop 0
	v_addc_co_u32_e32 v155, vcc, 0, v133, vcc
	ds_read_b128 v[132:135], v230 offset:512
	v_cvt_f32_i32_e32 v124, v124
	v_cvt_f32_i32_e32 v127, v127
	v_cvt_f32_i32_e32 v126, v126
	v_cvt_f32_i32_e32 v121, v121
	v_cvt_f32_i32_e32 v120, v120
	v_cvt_f32_i32_e32 v123, v123
	v_cvt_f32_i32_e32 v122, v122
	v_cvt_f32_i32_e32 v117, v117
	v_cvt_f32_i32_e32 v116, v116
	v_cvt_f32_i32_e32 v119, v119
	v_cvt_f32_i32_e32 v118, v118
	v_cvt_f32_i32_e32 v113, v113
	v_cvt_f32_i32_e32 v112, v112
	v_cvt_f32_i32_e32 v115, v115
	v_cvt_f32_i32_e32 v114, v114
	v_cvt_f32_i32_e32 v109, v109
	v_cvt_f32_i32_e32 v108, v108
	v_cvt_f32_i32_e32 v111, v111
	v_cvt_f32_i32_e32 v110, v110
	v_cvt_f32_i32_e32 v105, v105
	v_cvt_f32_i32_e32 v104, v104
	v_cvt_f32_i32_e32 v107, v107
	v_cvt_f32_i32_e32 v106, v106
	v_cvt_f32_i32_e32 v103, v103
	v_cvt_f32_i32_e32 v102, v102
	v_cvt_f32_i32_e32 v101, v101
	v_cvt_f32_i32_e32 v100, v100
	v_cvt_f32_i32_e32 v77, v77
	v_cvt_f32_i32_e32 v76, v76
	v_cvt_f32_i32_e32 v79, v79
	v_cvt_f32_i32_e32 v78, v78
	s_waitcnt lgkmcnt(0)
	v_pk_mul_f32 v[128:129], v[144:145], v[134:135] op_sel_hi:[0,1]
	v_pk_mul_f32 v[156:157], v[144:145], v[132:133] op_sel_hi:[0,1]
	v_pk_mul_f32 v[130:131], v[128:129], v[126:127]
	v_pk_mul_f32 v[128:129], v[156:157], v[124:125]
	v_pk_mul_f32 v[124:125], v[148:149], v[134:135] op_sel_hi:[0,1]
	v_pk_mul_f32 v[156:157], v[148:149], v[132:133] op_sel_hi:[0,1]
	v_pk_mul_f32 v[126:127], v[124:125], v[122:123]
	v_pk_mul_f32 v[124:125], v[156:157], v[120:121]
	v_pk_mul_f32 v[120:121], v[142:143], v[134:135] op_sel_hi:[0,1]
	v_pk_mul_f32 v[156:157], v[142:143], v[132:133] op_sel_hi:[0,1]
	v_pk_mul_f32 v[122:123], v[120:121], v[118:119]
	v_pk_mul_f32 v[120:121], v[156:157], v[116:117]
	v_pk_mul_f32 v[116:117], v[150:151], v[134:135] op_sel_hi:[0,1]
	v_pk_mul_f32 v[156:157], v[150:151], v[132:133] op_sel_hi:[0,1]
	v_pk_mul_f32 v[118:119], v[116:117], v[114:115]
	v_pk_mul_f32 v[116:117], v[156:157], v[112:113]
	v_pk_mul_f32 v[112:113], v[138:139], v[134:135] op_sel_hi:[0,1]
	v_pk_mul_f32 v[156:157], v[138:139], v[132:133] op_sel_hi:[0,1]
	v_pk_mul_f32 v[114:115], v[112:113], v[110:111]
	v_pk_mul_f32 v[112:113], v[156:157], v[108:109]
	v_pk_mul_f32 v[108:109], v[152:153], v[134:135] op_sel_hi:[0,1]
	v_pk_mul_f32 v[156:157], v[152:153], v[132:133] op_sel_hi:[0,1]
	v_pk_mul_f32 v[110:111], v[108:109], v[106:107]
	v_pk_mul_f32 v[108:109], v[156:157], v[104:105]
	v_pk_mul_f32 v[104:105], v[136:137], v[134:135] op_sel_hi:[0,1]
	v_pk_mul_f32 v[106:107], v[136:137], v[132:133] op_sel_hi:[0,1]
	v_pk_mul_f32 v[102:103], v[104:105], v[102:103]
	v_pk_mul_f32 v[104:105], v[146:147], v[134:135] op_sel_hi:[0,1]
	v_pk_mul_f32 v[132:133], v[146:147], v[132:133] op_sel_hi:[0,1]
	v_pk_mul_f32 v[100:101], v[106:107], v[100:101]
	v_pk_mul_f32 v[106:107], v[104:105], v[78:79]
	v_pk_mul_f32 v[104:105], v[132:133], v[76:77]
	s_nop 0
	ds_read_b128 v[132:135], v230 offset:528
	v_cvt_f32_i32_e32 v69, v69
	v_cvt_f32_i32_e32 v68, v68
	v_cvt_f32_i32_e32 v71, v71
	v_cvt_f32_i32_e32 v70, v70
	v_cvt_f32_i32_e32 v61, v61
	v_cvt_f32_i32_e32 v60, v60
	v_cvt_f32_i32_e32 v63, v63
	v_cvt_f32_i32_e32 v62, v62
	v_cvt_f32_i32_e32 v45, v45
	v_cvt_f32_i32_e32 v44, v44
	v_cvt_f32_i32_e32 v47, v47
	v_cvt_f32_i32_e32 v46, v46
	v_cvt_f32_i32_e32 v41, v41
	v_cvt_f32_i32_e32 v40, v40
	v_cvt_f32_i32_e32 v43, v43
	v_cvt_f32_i32_e32 v42, v42
	v_cvt_f32_i32_e32 v33, v33
	v_cvt_f32_i32_e32 v32, v32
	v_cvt_f32_i32_e32 v35, v35
	v_cvt_f32_i32_e32 v34, v34
	v_cvt_f32_i32_e32 v37, v37
	v_cvt_f32_i32_e32 v36, v36
	v_cvt_f32_i32_e32 v39, v39
	v_cvt_f32_i32_e32 v38, v38
	s_waitcnt lgkmcnt(0)
	v_pk_mul_f32 v[76:77], v[144:145], v[134:135] op_sel_hi:[0,1]
	v_pk_mul_f32 v[144:145], v[144:145], v[132:133] op_sel_hi:[0,1]
	v_pk_mul_f32 v[78:79], v[76:77], v[70:71]
	v_pk_mul_f32 v[76:77], v[144:145], v[68:69]
	v_cvt_f32_i32_e32 v69, v73
	v_cvt_f32_i32_e32 v68, v72
	v_cvt_f32_i32_e32 v71, v75
	v_cvt_f32_i32_e32 v70, v74
	v_pk_mul_f32 v[72:73], v[148:149], v[134:135] op_sel_hi:[0,1]
	v_pk_mul_f32 v[144:145], v[148:149], v[132:133] op_sel_hi:[0,1]
	v_pk_mul_f32 v[74:75], v[72:73], v[70:71]
	v_pk_mul_f32 v[72:73], v[144:145], v[68:69]
	v_cvt_f32_i32_e32 v69, v81
	v_cvt_f32_i32_e32 v68, v80
	v_cvt_f32_i32_e32 v71, v83
	v_cvt_f32_i32_e32 v70, v82
	v_pk_mul_f32 v[80:81], v[142:143], v[134:135] op_sel_hi:[0,1]
	v_pk_mul_f32 v[82:83], v[142:143], v[132:133] op_sel_hi:[0,1]
	v_pk_mul_f32 v[68:69], v[82:83], v[68:69]
	v_pk_mul_f32 v[70:71], v[80:81], v[70:71]
	v_pk_mul_f32 v[80:81], v[150:151], v[134:135] op_sel_hi:[0,1]
	v_pk_mul_f32 v[82:83], v[150:151], v[132:133] op_sel_hi:[0,1]
	v_pk_mul_f32 v[62:63], v[80:81], v[62:63]
	v_pk_mul_f32 v[60:61], v[82:83], v[60:61]
	v_pk_mul_f32 v[80:81], v[138:139], v[134:135] op_sel_hi:[0,1]
	v_pk_mul_f32 v[82:83], v[138:139], v[132:133] op_sel_hi:[0,1]
	v_pk_mul_f32 v[46:47], v[80:81], v[46:47]
	v_pk_mul_f32 v[44:45], v[82:83], v[44:45]
	v_pk_mul_f32 v[80:81], v[152:153], v[134:135] op_sel_hi:[0,1]
	v_pk_mul_f32 v[82:83], v[152:153], v[132:133] op_sel_hi:[0,1]
	v_pk_mul_f32 v[42:43], v[80:81], v[42:43]
	v_pk_mul_f32 v[40:41], v[82:83], v[40:41]
	v_pk_mul_f32 v[80:81], v[136:137], v[134:135] op_sel_hi:[0,1]
	v_pk_mul_f32 v[82:83], v[136:137], v[132:133] op_sel_hi:[0,1]
	v_pk_mul_f32 v[34:35], v[80:81], v[34:35]
	v_pk_mul_f32 v[32:33], v[82:83], v[32:33]
	v_pk_mul_f32 v[80:81], v[146:147], v[134:135] op_sel_hi:[0,1]
	v_pk_mul_f32 v[82:83], v[146:147], v[132:133] op_sel_hi:[0,1]
	v_pk_mul_f32 v[38:39], v[80:81], v[38:39]
	v_pk_mul_f32 v[36:37], v[82:83], v[36:37]
	s_nop 0
	v_cmp_gt_i32_e32 vcc, s94, v149
	s_and_saveexec_b64 s[6:7], vcc
	s_cbranch_execz .LBB0_809
	s_movk_i32 s5, 0x80
	v_cmp_gt_i32_e32 vcc, s5, v149
	s_add_i32 s5, s4, 0x2a80
	v_mov_b32_e32 v80, s5
	v_mov_b32_e32 v81, s4
	v_cndmask_b32_e32 v80, v80, v81, vcc
	v_add_u32_e32 v80, v80, v149
	v_ashrrev_i32_e32 v81, 31, v80
	v_readlane_b32 s8, v251, 21
	v_lshlrev_b64 v[80:81], 2, v[80:81]
	v_readlane_b32 s22, v251, 35
	v_readlane_b32 s23, v251, 36
	v_lshl_add_u32 v132, v149, 2, 0
	v_readlane_b32 s9, v251, 22
	v_lshl_add_u64 v[82:83], s[22:23], 0, v[80:81]
	v_readlane_b32 s10, v251, 23
	v_readlane_b32 s11, v251, 24
	v_readlane_b32 s12, v251, 25
	v_readlane_b32 s13, v251, 26
	v_readlane_b32 s14, v251, 27
	v_readlane_b32 s15, v251, 28
	v_readlane_b32 s16, v251, 29
	v_readlane_b32 s17, v251, 30
	v_readlane_b32 s18, v251, 31
	v_readlane_b32 s19, v251, 32
	v_readlane_b32 s20, v251, 33
	v_readlane_b32 s21, v251, 34
	v_add_u32_e32 v135, 0x20000, v132
	v_add_co_u32_e32 v132, vcc, 0x15000, v82
	v_readlane_b32 s8, v251, 5
	s_nop 0
	v_addc_co_u32_e32 v133, vcc, 0, v83, vcc
	v_readlane_b32 s9, v251, 6
	v_add_co_u32_e32 v82, vcc, 0x2b000, v82
	v_lshl_add_u64 v[80:81], s[8:9], 0, v[80:81]
	s_nop 0
	v_addc_co_u32_e32 v83, vcc, 0, v83, vcc
	v_readlane_b32 s10, v251, 7
	v_readlane_b32 s11, v251, 8
	v_readlane_b32 s12, v251, 9
	v_readlane_b32 s13, v251, 10
	v_readlane_b32 s14, v251, 11
	v_readlane_b32 s15, v251, 12
	v_readlane_b32 s16, v251, 13
	v_readlane_b32 s17, v251, 14
	v_readlane_b32 s18, v251, 15
	v_readlane_b32 s19, v251, 16
	v_readlane_b32 s20, v251, 17
	v_readlane_b32 s21, v251, 18
	v_readlane_b32 s22, v251, 19
	v_readlane_b32 s23, v251, 20
	ds_write2st64_b32 v135, v232, v233 offset1:4
	ds_write2st64_b32 v135, v234, v235 offset0:8 offset1:12
